# hg scan: XOR-swizzled K^T/V^T LDS images (transposing writes 2-way instead of 8-way bank conflicted)
# baseline (speedup 1.0000x reference)
; __device__ __forceinline__ int TID() { int t = threadIdx.x; asm volatile("" : "+v"(t)); return t; }
; __device__ __forceinline__ int BID() { int t = blockIdx.x; asm volatile("" : "+s"(t)); return t; }
; __device__ __forceinline__ unsigned cvt_pk_bf16(float lo, float hi) { unsigned r; asm("v_cvt_pk_bf16_f32 %0, %1, %2" : "=v"(r) : "v"(lo), "v"(hi)); return r; }
; __device__ __forceinline__ void hg_block(ArgsP a_, int jl, unsigned char* smem) { const ArgsP a = a_;
;     constexpr int LQ = 136, LJ = 72;
;     bf16_t* QA = (bf16_t*)smem; bf16_t* KB = (bf16_t*)(smem + 17408); bf16_t* QS = (bf16_t*)(smem + 34816); bf16_t* KT = (bf16_t*)(smem + 52224); bf16_t* VT = (bf16_t*)(smem + 70656);
;     bf16_t* ST = (bf16_t*)(smem + 89088); bf16_t* P = (bf16_t*)(smem + 123904); float* GI = (float*)(smem + 133120); float* SDEC = (float*)(smem + 133376);
;     float* TOT = (float*)(smem + 133888);   float* RSm = (float*)(smem + 142080);
;     const int tid = TID(), wid = tid >> 6, lane = tid & 63, fr = lane & 15, fq = lane >> 4;
;     const int G = gridDim.x, cb = BID();
;     const unsigned char* proj = a->ws + B_PROJ;
;     const bf16_t* Qg = (const bf16_t*)proj; const float* LFg = (const float*)(proj + (size_t)MP * 2048); const bf16_t* Vg = (const bf16_t*)(proj + (size_t)MP * 6144); const bf16_t* Gg = (const bf16_t*)(proj + (size_t)MP * 8192);
;     const bf16_t* KKg = (const bf16_t*)(proj + (size_t)MP * 10240);
;     bf16_t* ON = (bf16_t*)(a->ws + B_ACT);
;     const float* ng = AIN(14) + (size_t)jl * 1024;
;     const int nunits = cb < 64 ? 33 : (1024 - (cb - 64) + (G - 64) - 1) / (G - 64);
;     const int c4 = (tid & 31) * 4, rg = tid >> 5, m = wid >> 1, hw = wid & 1, irow = 16 * m + fr;
;     f32x4 S[1][8]; f32x4 O[4];
;     f32x4 lf4[4]; u32x2 kk2[4], q2[4], v2[4]; u32x2 gpre[4];
;     ...
;               *(u32x2*)(KT + (c4 + e) * LJ + 4 * rg) = (u32x2){cvt_pk_bf16(ktv[0][e], ktv[1][e]), cvt_pk_bf16(ktv[2][e], ktv[3][e])};
;               unsigned vv[4];
; #pragma unroll
;               for (int r = 0; r < 4; ++r) { const unsigned w = (e < 2) ? v2[r].x : v2[r].y; vv[r] = (e & 1) ? (w >> 16) : (w & 0xffffu); }
;               *(u32x2*)(VT + (c4 + e) * LJ + 4 * rg) = (u32x2){vv[0] | (vv[1] << 16), vv[2] | (vv[3] << 16)}; }
.LBB0_388:
	v_and_b32_e32 v92, 15, v22
	s_andn2_b64 vcc, exec, s[46:47]
	s_cbranch_vccnz .LBB0_442
	v_readlane_b32 s46, v254, 62
	v_readlane_b32 s47, v254, 63
	s_mov_b32 s60, s46
	s_mov_b32 s61, s12
	s_lshl_b64 s[46:47], s[60:61], 12
	s_add_u32 s44, s44, 0x12000000
	v_writelane_b32 v255, s44, 8
	s_addc_u32 s44, s45, 0
	s_add_u32 s48, s42, s46
	v_writelane_b32 v255, s44, 9
	s_addc_u32 s49, s43, s47
	s_lshl_b64 s[42:43], s[60:61], 10
	v_writelane_b32 v255, s42, 10
	v_lshlrev_b32_e32 v26, 2, v93
	s_sub_i32 s59, s50, 64
	v_writelane_b32 v255, s43, 11
	v_readlane_b32 s42, v254, 38
	v_readlane_b32 s50, v254, 41
	v_ashrrev_i32_e32 v29, 7, v22
	v_lshl_add_u32 v27, v25, 2, s42
	v_readlane_b32 s42, v254, 39
	v_lshlrev_b32_e32 v32, 1, v25
	v_lshlrev_b32_e32 v20, 2, v24
	v_add_u32_e32 v135, s42, v26
	v_cmp_gt_u32_e64 s[42:43], 32, v22
	v_add_u32_e32 v137, s50, v26
	v_lshlrev_b32_e32 v26, 6, v25
	v_writelane_b32 v255, s42, 12
	v_cmp_le_i32_e64 s[44:45], v32, v29
	v_cmp_lt_i32_e64 s[46:47], v32, v29
	v_writelane_b32 v255, s43, 13
	s_add_i32 s42, 0, 0x20800
	v_lshlrev_b32_e32 v32, 4, v24
	v_lshlrev_b32_e32 v34, 5, v25
	v_lshlrev_b32_e32 v25, 7, v25
	v_lshl_or_b32 v31, v29, 4, v92
	v_add3_u32 v141, s42, v32, v25
	v_or_b32_e32 v25, v34, v20
	v_cmp_gt_i32_e64 s[62:63], v25, v31
	v_or_b32_e32 v35, v34, v92
	v_or_b32_e32 v34, 2, v25
	v_writelane_b32 v255, s62, 14
	v_ashrrev_i32_e32 v21, 6, v22
	v_lshlrev_b32_e32 v28, 4, v21
	v_writelane_b32 v255, s63, 15
	v_cmp_lt_i32_e64 s[62:63], v25, v31
	v_lshlrev_b32_e32 v21, 5, v21
	v_lshlrev_b32_e32 v30, 3, v24
	v_writelane_b32 v255, s62, 16
	v_readlane_b32 s43, v254, 36
	v_readlane_b32 s51, v254, 42
	v_writelane_b32 v255, s63, 17
	v_cmp_gt_i32_e64 s[62:63], v34, v31
	v_or_b32_e32 v34, 3, v25
	v_add3_u32 v21, s43, v21, v30
	v_writelane_b32 v255, s62, 18
	v_add_u32_e32 v33, s43, v32
	s_movk_i32 s43, 0x90
	v_writelane_b32 v255, s63, 19
	v_cmp_gt_i32_e64 s[62:63], v34, v31
	v_or_b32_e32 v34, 16, v25
	v_mul_lo_u32 v36, v31, s43
	v_writelane_b32 v255, s62, 20
	v_add_u32_e32 v36, s51, v36
	v_lshl_add_u32 v142, v25, 1, v36
	v_writelane_b32 v255, s63, 21
	v_cmp_gt_i32_e64 s[62:63], v34, v31
	s_movk_i32 s53, 0x110
	v_and_b32_e32 v22, 0xffffffc0, v22
	v_writelane_b32 v255, s62, 22
	v_lshl_add_u32 v138, v31, 2, s42
	v_mul_lo_u32 v29, v31, s53
	v_writelane_b32 v255, s63, 23
	v_cmp_lt_i32_e64 s[62:63], v34, v31
	v_or_b32_e32 v34, 18, v25
	v_or_b32_e32 v25, 19, v25
	v_writelane_b32 v255, s62, 24
	v_readlane_b32 s54, v254, 40
	v_lshl_add_u32 v16, v93, 1, 0
	v_writelane_b32 v255, s63, 25
	v_cmp_gt_i32_e64 s[62:63], v34, v31
	v_lshlrev_b32_e32 v136, 2, v23
	v_or_b32_e32 v18, v20, v28
	v_writelane_b32 v255, s62, 26
	s_ashr_i32 s57, s13, 3
	s_sub_i32 s55, s13, 64
	v_writelane_b32 v255, s63, 27
	v_cmp_gt_i32_e64 s[62:63], v25, v31
	v_add_u32_e32 v31, s50, v22
	v_or_b32_e32 v22, v28, v92
	v_writelane_b32 v255, s62, 28
	s_mov_b32 s50, s60
	v_mul_lo_u32 v22, v22, s43
	v_writelane_b32 v255, s63, 29
	v_cmp_eq_u32_e64 s[42:43], 0, v24
	v_writelane_b32 v254, s50, 62
	v_ashrrev_i32_e32 v19, 31, v18
	v_writelane_b32 v255, s42, 30
	v_writelane_b32 v254, s51, 63
	s_movk_i32 s50, 0x440
	v_writelane_b32 v255, s43, 31
	v_mad_u64_u32 v[106:107], s[50:51], v23, s50, v[16:17]
	v_readlane_b32 s42, v255, 4
	v_or_b32_e32 v107, 1, v136
	v_readlane_b32 s43, v255, 5
	v_mad_u64_u32 v[108:109], s[50:51], v107, s53, v[16:17]
	v_mul_u32_u24_e32 v16, 0x48, v93
	v_lshlrev_b64 v[96:97], 9, v[18:19]
	v_lshlrev_b32_e32 v18, 3, v23
	v_add3_u32 v144, 0, v22, v32
	v_or_b32_e32 v22, v26, v20
	s_and_b64 s[42:43], s[42:43], exec
	v_lshlrev_b32_e32 v16, 1, v16
	s_mov_b32 s42, 0x1300000
	v_add3_u32 v166, 0, v18, v16
	v_add3_u32 v167, s54, v18, v16
	v_lshlrev_b32_e32 v16, 2, v22
	s_cselect_b32 s52, s42, 0x1100000
	s_cselect_b32 s42, 7, 3
	v_lshl_add_u64 v[114:115], s[48:49], 0, v[16:17]
	s_add_i32 s48, s56, -1
	v_add3_u32 v139, 0, v29, v32
	v_or_b32_e32 v29, v26, v92
	v_mul_u32_u24_e32 v35, 0x110, v35
	v_writelane_b32 v255, s48, 32
	s_lshl_b32 s48, s52, 2
	v_lshlrev_b32_e32 v19, 9, v23
	v_mul_u32_u24_e32 v30, 0x110, v92
	v_add3_u32 v140, 0, v35, v32
	v_mul_u32_u24_e32 v35, 0x110, v29
	v_add_u32_e32 v25, s54, v32
	v_mul_u32_u24_e32 v29, 0x90, v29
	v_mul_u32_u24_e32 v28, 0x90, v92
	v_lshlrev_b32_e32 v145, 3, v134
	v_mov_b32_e32 v18, 0
	v_writelane_b32 v255, s48, 33
	s_mul_i32 s58, s57, 0x810
	v_add_u32_e32 v143, v36, v32
	s_mov_b32 s65, 0
	s_lshl_b64 s[42:43], s[60:61], s42
	v_cmp_lt_i32_e64 s[66:67], 0, v23
	v_cmp_lt_i32_e64 s[68:69], 1, v23
	v_cmp_lt_i32_e64 s[70:71], 2, v23
	v_cmp_lt_i32_e64 s[72:73], 3, v23
	v_cmp_lt_i32_e64 s[74:75], 4, v23
	v_cmp_lt_i32_e64 s[76:77], 5, v23
	v_cmp_lt_i32_e64 s[78:79], 6, v23
	v_cmp_lt_i32_e64 s[80:81], 7, v23
	v_cmp_lt_i32_e64 s[82:83], 8, v23
	v_cmp_lt_i32_e64 s[84:85], 9, v23
	v_cmp_lt_i32_e64 s[86:87], 10, v23
	v_cmp_lt_i32_e64 s[88:89], 11, v23
	v_cmp_lt_i32_e64 s[90:91], 12, v23
	v_cmp_lt_i32_e64 s[92:93], 13, v23
	v_cmp_lt_i32_e64 s[94:95], 14, v23
	v_cmp_lt_i32_e64 s[96:97], 15, v23
	v_or_b32_e32 v109, 2, v136
	v_add_u32_e32 v147, 0x110, v108
	v_or_b32_e32 v164, 3, v136
	v_add_u32_e32 v165, 0x220, v108
	v_add_u32_e32 v168, v135, v19
	v_lshlrev_b32_e32 v116, 1, v20
	v_lshlrev_b32_e32 v118, 1, v26
	v_add_u32_e32 v169, v21, v30
	v_add_u32_e32 v170, v25, v29
	v_add_u32_e32 v171, v31, v32
	v_add_u32_e32 v172, v25, v28
	v_and_b32_e32 v202, 15, v186
	v_lshrrev_b32_e32 v202, 3, v202
	v_bfe_u32 v203, v186, 4, 2
	v_lshrrev_b32_e32 v204, 6, v186
	v_lshl_add_u32 v205, v204, 1, v202
	v_and_b32_e32 v205, 3, v205
	v_xor_b32_e32 v205, v203, v205
	v_sub_u32_e32 v205, v205, v203
	v_lshl_add_u32 v144, v205, 4, v144
	v_xor_b32_e32 v205, v203, v202
	v_sub_u32_e32 v205, v205, v203
	v_lshl_add_u32 v184, v205, 4, v170
	v_lshl_add_u32 v250, v205, 4, v172
	v_or_b32_e32 v205, 2, v202
	v_xor_b32_e32 v205, v203, v205
	v_sub_u32_e32 v205, v205, v203
	v_lshl_add_u32 v185, v205, 4, v170
	v_lshl_add_u32 v251, v205, 4, v172
	v_bfe_u32 v205, v186, 1, 2
	v_and_b32_e32 v204, 3, v204
	v_xor_b32_e32 v205, v204, v205
	v_sub_u32_e32 v205, v205, v204
	v_lshl_add_u32 v166, v205, 4, v166
	v_lshl_add_u32 v167, v205, 4, v167
	v_add_u32_e32 v173, v27, v145
	v_lshlrev_b32_e32 v122, 1, v22
	v_add_u32_e32 v174, v33, v35
	v_writelane_b32 v255, s55, 34
	s_mov_b32 s60, s55
	v_mov_b32_e32 v19, v18
	v_mov_b32_e32 v20, v18
	v_mov_b32_e32 v21, v18
	v_mov_b32_e32 v22, v18
	v_mov_b32_e32 v23, v18
	v_mov_b32_e32 v24, v18
	v_mov_b32_e32 v25, v18
	v_mov_b32_e32 v26, v18
	v_mov_b32_e32 v27, v18
	v_mov_b32_e32 v28, v18
	v_mov_b32_e32 v29, v18
	v_mov_b32_e32 v30, v18
	v_mov_b32_e32 v31, v18
	v_mov_b32_e32 v32, v18
	v_mov_b32_e32 v33, v18
	v_mov_b32_e32 v34, v18
	v_mov_b32_e32 v35, v18
	v_mov_b32_e32 v36, v18
	v_mov_b32_e32 v37, v18
	v_mov_b32_e32 v38, v18
	v_mov_b32_e32 v39, v18
	v_mov_b32_e32 v40, v18
	v_mov_b32_e32 v41, v18
	v_mov_b32_e32 v42, v18
	v_mov_b32_e32 v43, v18
	v_mov_b32_e32 v44, v18
	v_mov_b32_e32 v45, v18
	v_mov_b32_e32 v46, v18
	v_mov_b32_e32 v47, v18
	v_mov_b32_e32 v48, v18
	v_mov_b32_e32 v49, v18
	s_branch .LBB0_391

; __device__ __forceinline__ unsigned cvt_pk_bf16(float lo, float hi) { unsigned r; asm("v_cvt_pk_bf16_f32 %0, %1, %2" : "=v"(r) : "v"(lo), "v"(hi)); return r; }
; template <int DK, int DV, bool SEPQ> ...
;     ...
;         for (int vt = 0; vt < NVT; ++vt) { const f32x4 s = S[ct][vt]; u32x2 w; w.x = cvt_pk_bf16(s[0], s[1]); w.y = cvt_pk_bf16(s[2], s[3]);
;             *(u32x2*)(ST + (16 * vt + fr) * LQ + 16 * (wid * NCTW + ct) + 4 * fq) = w; }
;     __syncthreads();
;     {
;         const float gi_i = GI[16 * m + fr];
;         const int n0 = 2 * hw, n1 = 2 * hw + 1; const bool do0 = n0 <= m, do1 = n1 <= m;
;         f32x4 acc0 = {0.f, 0.f, 0.f, 0.f}, acc1 = {0.f, 0.f, 0.f, 0.f};
; #pragma unroll
;         for (int vt = 0; vt < NVTW; ++vt) O[vt] = (f32x4){0.f, 0.f, 0.f, 0.f};
; #pragma unroll
;         for (int ks = 0; ks < DK / 32; ++ks) {
;             const bf16x8 qf = *(const bf16x8*)(QA + (16 * m + fr) * LQ + 32 * ks + 8 * fq);
;             if (do0) { const bf16x8 kf = *(const bf16x8*)(KB + (16 * n0 + fr) * LQ + 32 * ks + 8 * fq); acc0 = __builtin_amdgcn_mfma_f32_16x16x32_bf16(kf, qf, acc0, 0, 0, 0); }
;             if (do1) { const bf16x8 kf = *(const bf16x8*)(KB + (16 * n1 + fr) * LQ + 32 * ks + 8 * fq); acc1 = __builtin_amdgcn_mfma_f32_16x16x32_bf16(kf, qf, acc1, 0, 0, 0); }
;             bf16x8 qs = qf; if (SEPQ) qs = *(const bf16x8*)(QS + (16 * m + fr) * LQ + 32 * ks + 8 * fq);
; #pragma unroll
;             for (int vt = 0; vt < NVTW; ++vt) { const bf16x8 sf = *(const bf16x8*)(ST + (16 * (hw * NVTW + vt) + fr) * LQ + 32 * ks + 8 * fq); O[vt] = __builtin_amdgcn_mfma_f32_16x16x32_bf16(sf, qs, O[vt], 0, 0, 0); }
;         }
; #pragma unroll
;         for (int nn = 0; nn < 2; ++nn) {
;             const int n = 2 * hw + nn; const f32x4 acc = nn == 0 ? acc0 : acc1;
;             const f32x4 gj = *(const f32x4*)(GI + 16 * n + 4 * fq); const int i = 16 * m + fr, j0 = 16 * n + 4 * fq; float p[4];
; #pragma unroll
;             for (int e = 0; e < 4; ++e) p[e] = (j0 + e <= i) ? acc[e] * __expf(gi_i - gj[e]) : 0.f;
;             u32x2 w; w.x = cvt_pk_bf16(p[0], p[1]); w.y = cvt_pk_bf16(p[2], p[3]); *(u32x2*)(P + (16 * m + fr) * LJ + j0) = w;
;         }
;         const float ei = __expf(gi_i);
; #pragma unroll
;         for (int vt = 0; vt < NVTW; ++vt) O[vt] = O[vt] * ei;
.LBB0_420:
	s_lshl_b32 s54, s62, 9
	s_mov_b32 s55, s12
	v_lshl_add_u64 v[218:219], v[114:115], 0, s[54:55]
	global_load_dwordx4 v[202:205], v[218:219], off
	global_load_dwordx4 v[206:209], v[218:219], off offset:64
	global_load_dwordx4 v[210:213], v[218:219], off offset:128
	global_load_dwordx4 v[214:217], v[218:219], off offset:192
	v_cvt_pk_bf16_f32 v50, v18, v19
	v_cvt_pk_bf16_f32 v51, v20, v21
	ds_write_b64 v169, v[50:51]
	v_cvt_pk_bf16_f32 v50, v22, v23
	v_cvt_pk_bf16_f32 v51, v24, v25
	ds_write_b64 v169, v[50:51] offset:4352
	v_cvt_pk_bf16_f32 v50, v26, v27
	v_cvt_pk_bf16_f32 v51, v28, v29
	ds_write_b64 v169, v[50:51] offset:8704
	v_cvt_pk_bf16_f32 v50, v30, v31
	v_cvt_pk_bf16_f32 v51, v32, v33
	ds_write_b64 v169, v[50:51] offset:13056
	v_cvt_pk_bf16_f32 v50, v34, v35
	v_cvt_pk_bf16_f32 v51, v36, v37
	ds_write_b64 v169, v[50:51] offset:17408
	v_cvt_pk_bf16_f32 v50, v38, v39
	v_cvt_pk_bf16_f32 v51, v40, v41
	ds_write_b64 v169, v[50:51] offset:21760
	v_cvt_pk_bf16_f32 v50, v42, v43
	v_cvt_pk_bf16_f32 v51, v44, v45
	ds_write_b64 v169, v[50:51] offset:26112
	v_cvt_pk_bf16_f32 v50, v46, v47
	v_cvt_pk_bf16_f32 v51, v48, v49
	ds_write_b64 v169, v[50:51] offset:30464
	s_waitcnt lgkmcnt(0)
	s_barrier
	ds_read_b32 v16, v138
	ds_read_b128 v[218:221], v139
	ds_read_b128 v[222:225], v140 offset:17408
	ds_read_b128 v[226:229], v140 offset:21760
	ds_read_b128 v[242:245], v139 offset:34816
	ds_read_b128 v[246:249], v174
	ds_read_b128 v[74:77], v174 offset:4352
	ds_read_b128 v[176:179], v174 offset:8704
	ds_read_b128 v[180:183], v174 offset:13056
	ds_read_b128 v[230:233], v139 offset:64
	ds_read_b128 v[234:237], v140 offset:17472
	ds_read_b128 v[238:241], v140 offset:21824
	s_waitcnt lgkmcnt(8)
	v_mfma_f32_16x16x32_bf16 v[54:57], v[222:225], v[218:221], 0
	v_mfma_f32_16x16x32_bf16 v[50:53], v[226:229], v[218:221], 0
	s_waitcnt lgkmcnt(3)
	v_mfma_f32_16x16x32_bf16 v[58:61], v[246:249], v[242:245], 0
	v_mfma_f32_16x16x32_bf16 v[62:65], v[74:77], v[242:245], 0
	v_mfma_f32_16x16x32_bf16 v[66:69], v[176:179], v[242:245], 0
	v_mfma_f32_16x16x32_bf16 v[70:73], v[180:183], v[242:245], 0
	ds_read_b128 v[242:245], v139 offset:34880
	ds_read_b128 v[246:249], v174 offset:64
	ds_read_b128 v[74:77], v174 offset:4416
	ds_read_b128 v[176:179], v174 offset:8768
	ds_read_b128 v[180:183], v174 offset:13120
	ds_read_b128 v[218:221], v139 offset:128
	ds_read_b128 v[222:225], v140 offset:17536
	ds_read_b128 v[226:229], v140 offset:21888
	s_waitcnt lgkmcnt(8)
	v_mfma_f32_16x16x32_bf16 v[54:57], v[234:237], v[230:233], v[54:57]
	v_mfma_f32_16x16x32_bf16 v[50:53], v[238:241], v[230:233], v[50:53]
	s_waitcnt lgkmcnt(3)
	v_mfma_f32_16x16x32_bf16 v[58:61], v[246:249], v[242:245], v[58:61]
	v_mfma_f32_16x16x32_bf16 v[62:65], v[74:77], v[242:245], v[62:65]
	v_mfma_f32_16x16x32_bf16 v[66:69], v[176:179], v[242:245], v[66:69]
	v_mfma_f32_16x16x32_bf16 v[70:73], v[180:183], v[242:245], v[70:73]
	ds_read_b128 v[242:245], v139 offset:34944
	ds_read_b128 v[246:249], v174 offset:128
	ds_read_b128 v[74:77], v174 offset:4480
	ds_read_b128 v[176:179], v174 offset:8832
	ds_read_b128 v[180:183], v174 offset:13184
	ds_read_b128 v[230:233], v139 offset:192
	ds_read_b128 v[234:237], v140 offset:17600
	ds_read_b128 v[238:241], v140 offset:21952
	s_waitcnt lgkmcnt(8)
	v_mfma_f32_16x16x32_bf16 v[54:57], v[222:225], v[218:221], v[54:57]
	v_mfma_f32_16x16x32_bf16 v[50:53], v[226:229], v[218:221], v[50:53]
	s_waitcnt lgkmcnt(3)
	v_mfma_f32_16x16x32_bf16 v[58:61], v[246:249], v[242:245], v[58:61]
	v_mfma_f32_16x16x32_bf16 v[62:65], v[74:77], v[242:245], v[62:65]
	v_mfma_f32_16x16x32_bf16 v[66:69], v[176:179], v[242:245], v[66:69]
	v_mfma_f32_16x16x32_bf16 v[70:73], v[180:183], v[242:245], v[70:73]
	ds_read_b128 v[242:245], v139 offset:35008
	ds_read_b128 v[246:249], v174 offset:192
	ds_read_b128 v[74:77], v174 offset:4544
	ds_read_b128 v[176:179], v174 offset:8896
	ds_read_b128 v[180:183], v174 offset:13248
	s_waitcnt lgkmcnt(5)
	v_mfma_f32_16x16x32_bf16 v[54:57], v[234:237], v[230:233], v[54:57]
	v_mfma_f32_16x16x32_bf16 v[50:53], v[238:241], v[230:233], v[50:53]
	s_waitcnt lgkmcnt(0)
	v_mfma_f32_16x16x32_bf16 v[58:61], v[246:249], v[242:245], v[58:61]
	v_mfma_f32_16x16x32_bf16 v[62:65], v[74:77], v[242:245], v[62:65]
	v_mfma_f32_16x16x32_bf16 v[66:69], v[176:179], v[242:245], v[66:69]
	v_mfma_f32_16x16x32_bf16 v[70:73], v[180:183], v[242:245], v[70:73]
	s_nop 7
	v_readlane_b32 s52, v255, 14
	v_readlane_b32 s53, v255, 15
	ds_read_b128 v[74:77], v141
	s_waitcnt lgkmcnt(0)
	v_sub_f32_e32 v74, v16, v74
	v_mul_f32_e32 v74, 0x3fb8aa3b, v74
	v_exp_f32_e32 v74, v74
	s_nop 0
	v_mul_f32_e32 v54, v54, v74
	v_sub_f32_e32 v74, v16, v75
	v_mul_f32_e32 v74, 0x3fb8aa3b, v74
	v_exp_f32_e32 v74, v74
	v_cndmask_b32_e64 v54, v54, 0, s[52:53]
	v_readlane_b32 s52, v255, 16
	v_readlane_b32 s53, v255, 17
	v_mul_f32_e32 v55, v55, v74
	v_sub_f32_e32 v74, v16, v76
	v_mul_f32_e32 v74, 0x3fb8aa3b, v74
	v_exp_f32_e32 v74, v74
	v_cndmask_b32_e64 v55, 0, v55, s[52:53]
	v_readlane_b32 s52, v255, 18
	v_readlane_b32 s53, v255, 19
	v_mul_f32_e32 v56, v56, v74
	v_sub_f32_e32 v74, v16, v77
	v_mul_f32_e32 v74, 0x3fb8aa3b, v74
	v_exp_f32_e32 v74, v74
	v_cndmask_b32_e64 v56, v56, 0, s[52:53]
	v_readlane_b32 s52, v255, 20
	v_readlane_b32 s53, v255, 21
	v_mul_f32_e32 v57, v57, v74
	v_cvt_pk_bf16_f32 v54, v54, v55
	s_nop 0
	v_cndmask_b32_e64 v57, v57, 0, s[52:53]
	v_cvt_pk_bf16_f32 v55, v56, v57
	ds_write_b64 v142, v[54:55]
	ds_read_b128 v[54:57], v141 offset:64
	v_readlane_b32 s52, v255, 22
	v_readlane_b32 s53, v255, 23
	s_waitcnt lgkmcnt(0)
	v_sub_f32_e32 v54, v16, v54
	v_mul_f32_e32 v54, 0x3fb8aa3b, v54
	v_exp_f32_e32 v54, v54
	s_nop 0
	v_mul_f32_e32 v50, v50, v54
	v_sub_f32_e32 v54, v16, v55
	v_mul_f32_e32 v54, 0x3fb8aa3b, v54
	v_exp_f32_e32 v54, v54
	v_cndmask_b32_e64 v50, v50, 0, s[52:53]
	v_readlane_b32 s52, v255, 24
	v_readlane_b32 s53, v255, 25
	v_mul_f32_e32 v51, v51, v54
	v_sub_f32_e32 v54, v16, v56
	v_mul_f32_e32 v54, 0x3fb8aa3b, v54
	v_exp_f32_e32 v54, v54
	v_cndmask_b32_e64 v51, 0, v51, s[52:53]
	v_readlane_b32 s52, v255, 26
	v_readlane_b32 s53, v255, 27
	v_mul_f32_e32 v52, v52, v54
	v_sub_f32_e32 v54, v16, v57
	v_mul_f32_e32 v54, 0x3fb8aa3b, v54
	v_exp_f32_e32 v54, v54
	v_mul_f32_e32 v16, 0x3fb8aa3b, v16
	v_exp_f32_e32 v16, v16
	v_cndmask_b32_e64 v52, v52, 0, s[52:53]
	v_readlane_b32 s52, v255, 28
	v_mul_f32_e32 v53, v53, v54
	v_readlane_b32 s53, v255, 29
	v_cvt_pk_bf16_f32 v50, v50, v51
	v_pk_mul_f32 v[54:55], v[16:17], v[62:63] op_sel_hi:[0,1]
	v_pk_mul_f32 v[56:57], v[16:17], v[64:65] op_sel_hi:[0,1]
	v_cndmask_b32_e64 v53, v53, 0, s[52:53]
	v_cvt_pk_bf16_f32 v51, v52, v53
	ds_write_b64 v142, v[50:51] offset:32
	v_pk_mul_f32 v[50:51], v[16:17], v[58:59] op_sel_hi:[0,1]
	v_pk_mul_f32 v[52:53], v[16:17], v[60:61] op_sel_hi:[0,1]
	v_pk_mul_f32 v[58:59], v[16:17], v[66:67] op_sel_hi:[0,1]
	v_pk_mul_f32 v[60:61], v[16:17], v[68:69] op_sel_hi:[0,1]
	v_pk_mul_f32 v[62:63], v[16:17], v[70:71] op_sel_hi:[0,1]
	v_pk_mul_f32 v[64:65], v[16:17], v[72:73] op_sel_hi:[0,1]
	s_waitcnt lgkmcnt(0)
	s_barrier
; template <int DK, int DV, bool SEPQ> ...
;     ...
; #pragma unroll
;     for (int ks = 0; ks < 2; ++ks) { const bf16x8 pf = *(const bf16x8*)(P + (16 * m + fr) * LJ + 32 * ks + 8 * fq);
; #pragma unroll
;         for (int vt = 0; vt < NVTW; ++vt) { const bf16x8 vf = *(const bf16x8*)(VT + (16 * (hw * NVTW + vt) + fr) * LJ + 32 * ks + 8 * fq); O[vt] = __builtin_amdgcn_mfma_f32_16x16x32_bf16(vf, pf, O[vt], 0, 0, 0); } }
; #pragma unroll
;     for (int ct = 0; ct < NCTW; ++ct) { const int ctg = wid * NCTW + ct; const f32x4 dec = *(const f32x4*)(SDEC + 16 * ctg + 4 * fq);
; #pragma unroll
;         for (int vt = 0; vt < NVT; ++vt) S[ct][vt] = S[ct][vt] * dec;
; #pragma unroll
;         for (int ks = 0; ks < 2; ++ks) { const bf16x8 kf = *(const bf16x8*)(KT + (16 * ctg + fr) * LJ + 32 * ks + 8 * fq);
; #pragma unroll
;             for (int vt = 0; vt < NVT; ++vt) { const bf16x8 vf = *(const bf16x8*)(VT2 + (16 * vt + fr) * LJ + 32 * ks + 8 * fq); S[ct][vt] = __builtin_amdgcn_mfma_f32_16x16x32_bf16(kf, vf, S[ct][vt], 0, 0, 0); } } }
; __device__ __forceinline__ void hg_block(ArgsP a_, int jl, unsigned char* smem) { const ArgsP a = a_;
;     ...
;         { float ss = 0.f;
; #pragma unroll
;           for (int vt = 0; vt < 4; ++vt) ss += (O[vt][0] * O[vt][0] + O[vt][1] * O[vt][1]) + (O[vt][2] * O[vt][2] + O[vt][3] * O[vt][3]);
;           ss += __shfl_xor(ss, 16); ss += __shfl_xor(ss, 32); if (fq == 0) RSm[irow * 2 + hw] = ss; }
	ds_read_b128 v[218:221], v143
	ds_read_b128 v[222:225], v143 offset:64
	ds_read_b128 v[226:229], v184
	ds_read_b128 v[230:233], v185 offset:2304
	ds_read_b128 v[234:237], v184 offset:4608
	ds_read_b128 v[238:241], v185 offset:6912
	ds_read_b128 v[242:245], v184 offset:64
	ds_read_b128 v[246:249], v185 offset:2368
	ds_read_b128 v[74:77], v184 offset:4672
	ds_read_b128 v[176:179], v185 offset:6976
	s_waitcnt lgkmcnt(7)
	v_mfma_f32_16x16x32_bf16 v[50:53], v[226:229], v[218:221], v[50:53]
	s_waitcnt lgkmcnt(6)
	v_mfma_f32_16x16x32_bf16 v[54:57], v[230:233], v[218:221], v[54:57]
	s_waitcnt lgkmcnt(5)
	v_mfma_f32_16x16x32_bf16 v[70:73], v[234:237], v[218:221], v[58:61]
	s_waitcnt lgkmcnt(4)
	v_mfma_f32_16x16x32_bf16 v[66:69], v[238:241], v[218:221], v[62:65]
	s_waitcnt lgkmcnt(3)
	v_mfma_f32_16x16x32_bf16 v[62:65], v[242:245], v[222:225], v[50:53]
	s_waitcnt lgkmcnt(2)
	v_mfma_f32_16x16x32_bf16 v[58:61], v[246:249], v[222:225], v[54:57]
	s_waitcnt lgkmcnt(1)
	v_mfma_f32_16x16x32_bf16 v[54:57], v[74:77], v[222:225], v[70:73]
	s_waitcnt lgkmcnt(0)
	v_mfma_f32_16x16x32_bf16 v[50:53], v[176:179], v[222:225], v[66:69]
	ds_read_b128 v[180:183], v171
	ds_read_b128 v[74:77], v144 offset:52224
	ds_read_b128 v[176:179], v144 offset:52288
	ds_read_b128 v[218:221], v250
	ds_read_b128 v[222:225], v251 offset:2304
	ds_read_b128 v[226:229], v250 offset:4608
	ds_read_b128 v[230:233], v251 offset:6912
	ds_read_b128 v[234:237], v250 offset:9216
	ds_read_b128 v[238:241], v251 offset:11520
	ds_read_b128 v[242:245], v250 offset:13824
	ds_read_b128 v[246:249], v251 offset:16128
	s_waitcnt lgkmcnt(10)
	v_pk_mul_f32 v[18:19], v[18:19], v[180:181]
	v_pk_mul_f32 v[20:21], v[20:21], v[182:183]
	v_pk_mul_f32 v[22:23], v[22:23], v[180:181]
	v_pk_mul_f32 v[24:25], v[24:25], v[182:183]
	v_pk_mul_f32 v[26:27], v[26:27], v[180:181]
	v_pk_mul_f32 v[28:29], v[28:29], v[182:183]
	v_pk_mul_f32 v[30:31], v[30:31], v[180:181]
	v_pk_mul_f32 v[32:33], v[32:33], v[182:183]
	v_pk_mul_f32 v[34:35], v[34:35], v[180:181]
	v_pk_mul_f32 v[36:37], v[36:37], v[182:183]
	v_pk_mul_f32 v[38:39], v[38:39], v[180:181]
	v_pk_mul_f32 v[40:41], v[40:41], v[182:183]
	v_pk_mul_f32 v[42:43], v[42:43], v[180:181]
	v_pk_mul_f32 v[44:45], v[44:45], v[182:183]
	v_pk_mul_f32 v[46:47], v[46:47], v[180:181]
	v_pk_mul_f32 v[48:49], v[48:49], v[182:183]
	v_mul_f32_e32 v16, v63, v63
	v_fmac_f32_e32 v16, v62, v62
	ds_read_b128 v[66:69], v250 offset:64
	ds_read_b128 v[70:73], v251 offset:2368
	s_waitcnt lgkmcnt(9)
	v_mfma_f32_16x16x32_bf16 v[18:21], v[74:77], v[218:221], v[18:21]
	ds_read_b128 v[218:221], v250 offset:4672
	s_waitcnt lgkmcnt(9)
	v_mfma_f32_16x16x32_bf16 v[22:25], v[74:77], v[222:225], v[22:25]
	ds_read_b128 v[222:225], v251 offset:6976
	s_waitcnt lgkmcnt(9)
	v_mfma_f32_16x16x32_bf16 v[26:29], v[74:77], v[226:229], v[26:29]
	ds_read_b128 v[226:229], v250 offset:9280
	s_waitcnt lgkmcnt(9)
	v_mfma_f32_16x16x32_bf16 v[30:33], v[74:77], v[230:233], v[30:33]
	ds_read_b128 v[230:233], v251 offset:11584
	s_waitcnt lgkmcnt(9)
	v_mfma_f32_16x16x32_bf16 v[34:37], v[74:77], v[234:237], v[34:37]
	ds_read_b128 v[234:237], v250 offset:13888
	s_waitcnt lgkmcnt(9)
	v_mfma_f32_16x16x32_bf16 v[38:41], v[74:77], v[238:241], v[38:41]
	ds_read_b128 v[238:241], v251 offset:16192
	s_waitcnt lgkmcnt(9)
	v_mfma_f32_16x16x32_bf16 v[42:45], v[74:77], v[242:245], v[42:45]
	s_waitcnt lgkmcnt(8)
	v_mfma_f32_16x16x32_bf16 v[46:49], v[74:77], v[246:249], v[46:49]
	s_waitcnt lgkmcnt(7)
	v_mfma_f32_16x16x32_bf16 v[18:21], v[176:179], v[66:69], v[18:21]
	s_waitcnt lgkmcnt(6)
	v_mfma_f32_16x16x32_bf16 v[22:25], v[176:179], v[70:73], v[22:25]
	s_waitcnt lgkmcnt(5)
	v_mfma_f32_16x16x32_bf16 v[26:29], v[176:179], v[218:221], v[26:29]
	s_waitcnt lgkmcnt(4)
	v_mfma_f32_16x16x32_bf16 v[30:33], v[176:179], v[222:225], v[30:33]
	s_waitcnt lgkmcnt(3)
	v_mfma_f32_16x16x32_bf16 v[34:37], v[176:179], v[226:229], v[34:37]
	s_waitcnt lgkmcnt(2)
	v_mfma_f32_16x16x32_bf16 v[38:41], v[176:179], v[230:233], v[38:41]
	s_waitcnt lgkmcnt(1)
	v_mfma_f32_16x16x32_bf16 v[42:45], v[176:179], v[234:237], v[42:45]
	s_waitcnt lgkmcnt(0)
	v_mfma_f32_16x16x32_bf16 v[46:49], v[176:179], v[238:241], v[46:49]
	s_nop 7
	v_mul_f32_e32 v66, v65, v65
	v_fmac_f32_e32 v66, v64, v64
	v_add_f32_e32 v16, v16, v66
	v_mul_f32_e32 v66, v59, v59
	v_mul_f32_e32 v67, v61, v61
	v_fmac_f32_e32 v66, v58, v58
	v_fmac_f32_e32 v67, v60, v60
	v_add_f32_e32 v66, v66, v67
	v_add_f32_e32 v16, v16, v66
	v_mul_f32_e32 v66, v55, v55
	v_mul_f32_e32 v67, v57, v57
	v_fmac_f32_e32 v66, v54, v54
	v_fmac_f32_e32 v67, v56, v56
	v_add_f32_e32 v66, v66, v67
	v_add_f32_e32 v16, v16, v66
	v_mul_f32_e32 v66, v51, v51
	v_mul_f32_e32 v67, v53, v53
	v_fmac_f32_e32 v66, v50, v50
	v_fmac_f32_e32 v67, v52, v52
	v_add_f32_e32 v66, v66, v67
	v_and_b32_e32 v67, 64, v188
	v_add_f32_e32 v16, v16, v66
	v_xor_b32_e32 v66, 16, v188
	v_add_u32_e32 v67, 64, v67
	v_cmp_lt_i32_e32 vcc, v66, v67
	s_nop 1
	v_cndmask_b32_e32 v66, v188, v66, vcc
	v_lshlrev_b32_e32 v66, 2, v66
	ds_bpermute_b32 v66, v66, v16
	s_waitcnt lgkmcnt(0)
	v_add_f32_e32 v16, v16, v66
	v_xor_b32_e32 v66, 32, v188
	v_cmp_lt_i32_e32 vcc, v66, v67
	s_nop 1
	v_cndmask_b32_e32 v66, v188, v66, vcc
	v_lshlrev_b32_e32 v66, 2, v66
	ds_bpermute_b32 v66, v66, v16
	s_mov_b64 s[52:53], exec
	v_readlane_b32 s54, v255, 30
	v_readlane_b32 s55, v255, 31
	s_and_b64 s[54:55], s[52:53], s[54:55]
	s_mov_b64 exec, s[54:55]
	s_cbranch_execz .LBB0_438
	s_waitcnt lgkmcnt(0)
	v_add_f32_e32 v16, v16, v66
	ds_write_b32 v173, v16
